# adds: LDS-DMA loads of the int8 up-projection K-loop use the SGPR-base + 32-bit lane offset form (no 64-bit VALU address adds in the loader stream)
# baseline (speedup 1.0000x reference)
; #define PG8_STAGE(bufoff, gbase, unused) do { _Pragma("unroll") for (int _i = 0; _i < 2; ++_i) \
;         __builtin_amdgcn_global_load_lds((const unsigned*)((const char*)(gbase) + voff + _i * 8192), (LAS unsigned*)(lds + (bufoff) + ldsw + _i * 8192), 16, 0, 0); } while (0)
; #define PG8_LDA(dst, b, h) do { _Pragma("unroll") for (int m = 0; m < 4; ++m) _Pragma("unroll") for (int k = 0; k < 2; ++k) dst[m][k] = *(const LAS bf16x8*)(lds + PG8_SA(b, h) + aoff + m * 2048 + (FP8 ? k * 16 : k * 1024)); } while (0)
; #define PG8_LDB(dst, b, h) do { _Pragma("unroll") for (int n = 0; n < 2; ++n) _Pragma("unroll") for (int k = 0; k < 2; ++k) dst[n][k] = *(const LAS bf16x8*)(lds + PG8_SB(b, h) + boff + n * 2048 + (FP8 ? k * 16 : k * 1024)); } while (0)
; #define PG8_WAIT_V(n) asm volatile("s_waitcnt vmcnt(" #n ")" ::: "memory")
; #define PG8_WAIT_L(n) asm volatile("s_waitcnt lgkmcnt(" #n ")" ::: "memory")
; #define PG8_BAR __builtin_amdgcn_s_barrier()
; #define PG8_SCHED __builtin_amdgcn_sched_barrier(0)
; template <class Epi, class Sched, bool ALIGN_EPI, bool SP2, int MODE  >
; __device__ __forceinline__ void gemm_phase(LAS unsigned char* lds, const Gemm g, const Sched S, const Epi E, unsigned long long& probe_acc, int epi_id, int wv) {
;     ...
;             PG8_LDB(B0, 0, 0); PG8_LDB(B1, 0, 1); PG8_SCHED; PG8_LDA(At, 0, 0); PG8_STAGE(PG8_SA(1, 1), a1 + hA, voffA);
;             PG8_WAIT_V(8); PG8_WAIT_L(0); PG8_BAR; PG8_MMA(0, 0, At, B0); PG8_MMA(0, 1, At, B1); PG8_BAR; PG8_SCHED;
;             PG8_LDA(At, 0, 1); PG8_STAGE(PG8_SB(0, 0), b2, voffB); PG8_STAGE(PG8_SB(0, 1), b2 + hB, voffB); PG8_STAGE(PG8_SA(0, 0), a2, voffA);
;             PG8_WAIT_V(8); PG8_WAIT_L(0); PG8_BAR; PG8_MMA(1, 0, At, B0); PG8_MMA(1, 1, At, B1); PG8_BAR; PG8_SCHED;
.LBB0_326:
	v_add_u32_e32 v0, s39, v212
	ds_read_b128 v[132:135], v0
	ds_read_b128 v[136:139], v0 offset:1024
	ds_read_b128 v[140:143], v0 offset:2048
	ds_read_b128 v[144:147], v0 offset:3072
	v_add_u32_e32 v0, s65, v212
	ds_read_b128 v[148:151], v0
	ds_read_b128 v[152:155], v0 offset:1024
	ds_read_b128 v[156:159], v0 offset:2048
	ds_read_b128 v[160:163], v0 offset:3072
	s_add_u32 s30, s28, 0x8000
	s_addc_u32 s31, s29, 0
	s_cmp_eq_u32 s14, 12
	s_cselect_b32 s23, s27, s31
	s_cselect_b32 s22, s46, s30
	s_cselect_b32 s21, vcc_lo, s17
	s_cselect_b32 s20, vcc_hi, s16
	ds_read_b128 v[164:167], v213
	ds_read_b128 v[168:171], v213 offset:1024
	ds_read_b128 v[172:175], v213 offset:2048
	ds_read_b128 v[176:179], v213 offset:3072
	ds_read_b128 v[180:183], v213 offset:4096
	ds_read_b128 v[190:193], v213 offset:5120
	ds_read_b128 v[196:199], v213 offset:6144
	ds_read_b128 v[200:203], v213 offset:7168
	s_add_u32 s98, s28, s80
	s_addc_u32 s99, s29, s81
	s_add_i32 m0, s85, 0xc000
	s_nop 0
	global_load_lds_dwordx4 v130, s[98:99]
	s_add_u32 s100, s28, s82
	s_addc_u32 s101, s29, s83
	s_add_i32 m0, s85, 0xe000
	s_nop 0
	global_load_lds_dwordx4 v130, s[100:101]
	s_waitcnt vmcnt(8)
	s_waitcnt lgkmcnt(0)
	s_setprio 1
	s_barrier
	v_mfma_i32_16x16x64_i8 v[126:129], v[132:135], v[164:167], v[126:129]
	v_mfma_i32_16x16x64_i8 v[102:105], v[140:143], v[164:167], v[102:105]
	v_mfma_i32_16x16x64_i8 v[122:125], v[132:135], v[172:175], v[122:125]
	v_mfma_i32_16x16x64_i8 v[94:97], v[140:143], v[172:175], v[94:97]
	v_mfma_i32_16x16x64_i8 v[118:121], v[132:135], v[180:183], v[118:121]
	v_mfma_i32_16x16x64_i8 v[46:49], v[140:143], v[180:183], v[46:49]
	v_mfma_i32_16x16x64_i8 v[110:113], v[132:135], v[196:199], v[110:113]
	v_mfma_i32_16x16x64_i8 v[38:41], v[140:143], v[196:199], v[38:41]
	v_mfma_i32_16x16x64_i8 v[126:129], v[136:139], v[168:171], v[126:129]
	v_mfma_i32_16x16x64_i8 v[102:105], v[144:147], v[168:171], v[102:105]
	v_mfma_i32_16x16x64_i8 v[122:125], v[136:139], v[176:179], v[122:125]
	v_mfma_i32_16x16x64_i8 v[94:97], v[144:147], v[176:179], v[94:97]
	v_mfma_i32_16x16x64_i8 v[118:121], v[136:139], v[190:193], v[118:121]
	v_mfma_i32_16x16x64_i8 v[46:49], v[144:147], v[190:193], v[46:49]
	v_mfma_i32_16x16x64_i8 v[110:113], v[136:139], v[200:203], v[110:113]
	v_mfma_i32_16x16x64_i8 v[38:41], v[144:147], v[200:203], v[38:41]
	v_mfma_i32_16x16x64_i8 v[114:117], v[148:151], v[164:167], v[114:117]
	v_mfma_i32_16x16x64_i8 v[82:85], v[156:159], v[164:167], v[82:85]
	v_mfma_i32_16x16x64_i8 v[106:109], v[148:151], v[172:175], v[106:109]
	v_mfma_i32_16x16x64_i8 v[74:77], v[156:159], v[172:175], v[74:77]
	v_mfma_i32_16x16x64_i8 v[98:101], v[148:151], v[180:183], v[98:101]
	v_mfma_i32_16x16x64_i8 v[42:45], v[156:159], v[180:183], v[42:45]
	v_mfma_i32_16x16x64_i8 v[90:93], v[148:151], v[196:199], v[90:93]
	v_mfma_i32_16x16x64_i8 v[34:37], v[156:159], v[196:199], v[34:37]
	v_mfma_i32_16x16x64_i8 v[114:117], v[152:155], v[168:171], v[114:117]
	v_mfma_i32_16x16x64_i8 v[82:85], v[160:163], v[168:171], v[82:85]
	v_mfma_i32_16x16x64_i8 v[106:109], v[152:155], v[176:179], v[106:109]
	v_mfma_i32_16x16x64_i8 v[74:77], v[160:163], v[176:179], v[74:77]
	v_mfma_i32_16x16x64_i8 v[98:101], v[152:155], v[190:193], v[98:101]
	v_mfma_i32_16x16x64_i8 v[42:45], v[160:163], v[190:193], v[42:45]
	v_mfma_i32_16x16x64_i8 v[90:93], v[152:155], v[200:203], v[90:93]
	v_mfma_i32_16x16x64_i8 v[34:37], v[160:163], v[200:203], v[34:37]
	s_barrier
	s_setprio 0
	ds_read_b128 v[164:167], v213 offset:16384
	ds_read_b128 v[168:171], v213 offset:17408
	ds_read_b128 v[172:175], v213 offset:18432
	ds_read_b128 v[176:179], v213 offset:19456
	ds_read_b128 v[180:183], v213 offset:20480
	ds_read_b128 v[190:193], v213 offset:21504
	ds_read_b128 v[196:199], v213 offset:22528
	ds_read_b128 v[200:203], v213 offset:23552
	s_mov_b64 s[98:99], s[20:21]
	s_mov_b32 m0, s41
	s_nop 0
	global_load_lds_dwordx4 v130, s[98:99]
	s_add_u32 s100, s20, s70
	s_addc_u32 s101, s21, s71
	s_mov_b32 m0, s64
	s_nop 0
	global_load_lds_dwordx4 v130, s[100:101]
	s_add_u32 s98, s20, s72
	s_addc_u32 s99, s21, s73
	s_mov_b32 m0, s68
	s_nop 0
	global_load_lds_dwordx4 v130, s[98:99]
	s_add_u32 s100, s20, s74
	s_addc_u32 s101, s21, s75
	s_mov_b32 m0, s84
	s_nop 0
	global_load_lds_dwordx4 v130, s[100:101]
	s_mov_b64 s[98:99], s[22:23]
	s_mov_b32 m0, s85
	s_nop 0
	global_load_lds_dwordx4 v130, s[98:99]
	s_add_u32 s100, s22, s70
	s_addc_u32 s101, s23, s71
	s_mov_b32 m0, s86
	s_nop 0
	global_load_lds_dwordx4 v130, s[100:101]
	s_waitcnt vmcnt(8)
	s_waitcnt lgkmcnt(0)
	s_setprio 1
	s_barrier
	v_mfma_i32_16x16x64_i8 v[86:89], v[132:135], v[164:167], v[86:89]
	v_mfma_i32_16x16x64_i8 v[30:33], v[140:143], v[164:167], v[30:33]
	v_mfma_i32_16x16x64_i8 v[78:81], v[132:135], v[172:175], v[78:81]
	v_mfma_i32_16x16x64_i8 v[22:25], v[140:143], v[172:175], v[22:25]
	v_mfma_i32_16x16x64_i8 v[70:73], v[132:135], v[180:183], v[70:73]
	v_mfma_i32_16x16x64_i8 v[14:17], v[140:143], v[180:183], v[14:17]
	v_mfma_i32_16x16x64_i8 v[62:65], v[132:135], v[196:199], v[62:65]
	v_mfma_i32_16x16x64_i8 v[2:5], v[140:143], v[196:199], v[2:5]
	v_mfma_i32_16x16x64_i8 v[86:89], v[136:139], v[168:171], v[86:89]
	v_mfma_i32_16x16x64_i8 v[30:33], v[144:147], v[168:171], v[30:33]
	v_mfma_i32_16x16x64_i8 v[78:81], v[136:139], v[176:179], v[78:81]
	v_mfma_i32_16x16x64_i8 v[22:25], v[144:147], v[176:179], v[22:25]
	v_mfma_i32_16x16x64_i8 v[70:73], v[136:139], v[190:193], v[70:73]
	v_mfma_i32_16x16x64_i8 v[14:17], v[144:147], v[190:193], v[14:17]
	v_mfma_i32_16x16x64_i8 v[62:65], v[136:139], v[200:203], v[62:65]
	v_mfma_i32_16x16x64_i8 v[2:5], v[144:147], v[200:203], v[2:5]
	v_mfma_i32_16x16x64_i8 v[66:69], v[148:151], v[164:167], v[66:69]
	v_mfma_i32_16x16x64_i8 v[26:29], v[156:159], v[164:167], v[26:29]
	v_mfma_i32_16x16x64_i8 v[58:61], v[148:151], v[172:175], v[58:61]
	v_mfma_i32_16x16x64_i8 v[18:21], v[156:159], v[172:175], v[18:21]
	v_mfma_i32_16x16x64_i8 v[54:57], v[148:151], v[180:183], v[54:57]
	v_mfma_i32_16x16x64_i8 v[10:13], v[156:159], v[180:183], v[10:13]
	v_mfma_i32_16x16x64_i8 v[50:53], v[148:151], v[196:199], v[50:53]
	v_mfma_i32_16x16x64_i8 v[6:9], v[156:159], v[196:199], v[6:9]
	v_mfma_i32_16x16x64_i8 v[66:69], v[152:155], v[168:171], v[66:69]
	v_mfma_i32_16x16x64_i8 v[26:29], v[160:163], v[168:171], v[26:29]
	v_mfma_i32_16x16x64_i8 v[58:61], v[152:155], v[176:179], v[58:61]
	v_mfma_i32_16x16x64_i8 v[18:21], v[160:163], v[176:179], v[18:21]
	v_mfma_i32_16x16x64_i8 v[54:57], v[152:155], v[190:193], v[54:57]
	v_mfma_i32_16x16x64_i8 v[10:13], v[160:163], v[190:193], v[10:13]
	v_mfma_i32_16x16x64_i8 v[50:53], v[152:155], v[200:203], v[50:53]
	v_mfma_i32_16x16x64_i8 v[6:9], v[160:163], v[200:203], v[6:9]
	s_barrier
; #define PG8_STAGE(bufoff, gbase, unused) do { _Pragma("unroll") for (int _i = 0; _i < 2; ++_i) \
;         __builtin_amdgcn_global_load_lds((const unsigned*)((const char*)(gbase) + voff + _i * 8192), (LAS unsigned*)(lds + (bufoff) + ldsw + _i * 8192), 16, 0, 0); } while (0)
; #define PG8_LDA(dst, b, h) do { _Pragma("unroll") for (int m = 0; m < 4; ++m) _Pragma("unroll") for (int k = 0; k < 2; ++k) dst[m][k] = *(const LAS bf16x8*)(lds + PG8_SA(b, h) + aoff + m * 2048 + (FP8 ? k * 16 : k * 1024)); } while (0)
; #define PG8_LDB(dst, b, h) do { _Pragma("unroll") for (int n = 0; n < 2; ++n) _Pragma("unroll") for (int k = 0; k < 2; ++k) dst[n][k] = *(const LAS bf16x8*)(lds + PG8_SB(b, h) + boff + n * 2048 + (FP8 ? k * 16 : k * 1024)); } while (0)
; #define PG8_WAIT_V(n) asm volatile("s_waitcnt vmcnt(" #n ")" ::: "memory")
; #define PG8_WAIT_L(n) asm volatile("s_waitcnt lgkmcnt(" #n ")" ::: "memory")
; #define PG8_BAR __builtin_amdgcn_s_barrier()
; #define PG8_SCHED __builtin_amdgcn_sched_barrier(0)
; template <class Epi, class Sched, bool ALIGN_EPI, bool SP2, int MODE  >
; __device__ __forceinline__ void gemm_phase(LAS unsigned char* lds, const Gemm g, const Sched S, const Epi E, unsigned long long& probe_acc, int epi_id, int wv) {
;     ...
;             PG8_LDB(B0, 1, 0); PG8_LDB(B1, 1, 1); PG8_SCHED; PG8_LDA(At, 1, 0); PG8_STAGE(PG8_SA(0, 1), a2 + hA, voffA);
;             PG8_WAIT_V(8); PG8_WAIT_L(0); PG8_BAR; PG8_MMA(0, 0, At, B0); PG8_MMA(0, 1, At, B1); PG8_BAR; PG8_SCHED;
;             PG8_LDA(At, 1, 1); PG8_STAGE(PG8_SB(1, 0), b3, voffB); PG8_STAGE(PG8_SB(1, 1), b3 + hB, voffB); PG8_STAGE(PG8_SA(1, 0), a3, voffA);
;             PG8_WAIT_V(8); PG8_WAIT_L(0); PG8_BAR; PG8_MMA(1, 0, At, B0); PG8_MMA(1, 1, At, B1); PG8_BAR; PG8_SCHED;
	s_setprio 0
	v_add_u32_e32 v0, s90, v212
	ds_read_b128 v[132:135], v0
	ds_read_b128 v[136:139], v0 offset:1024
	ds_read_b128 v[140:143], v0 offset:2048
	ds_read_b128 v[144:147], v0 offset:3072
	v_add_u32_e32 v0, s95, v212
	ds_read_b128 v[148:151], v0
	ds_read_b128 v[152:155], v0 offset:1024
	ds_read_b128 v[156:159], v0 offset:2048
	ds_read_b128 v[160:163], v0 offset:3072
	ds_read_b128 v[164:167], v213 offset:32768
	ds_read_b128 v[168:171], v213 offset:33792
	ds_read_b128 v[172:175], v213 offset:34816
	ds_read_b128 v[176:179], v213 offset:35840
	ds_read_b128 v[180:183], v213 offset:36864
	ds_read_b128 v[190:193], v213 offset:37888
	ds_read_b128 v[196:199], v213 offset:38912
	ds_read_b128 v[200:203], v213 offset:39936
	s_add_u32 s98, s22, s72
	s_addc_u32 s99, s23, s73
	s_mov_b32 m0, s87
	s_nop 0
	global_load_lds_dwordx4 v130, s[98:99]
	s_add_u32 s100, s22, s74
	s_addc_u32 s101, s23, s75
	s_mov_b32 m0, s88
	s_nop 0
	global_load_lds_dwordx4 v130, s[100:101]
	s_waitcnt vmcnt(8)
	s_waitcnt lgkmcnt(0)
	s_setprio 1
	s_barrier
	v_mfma_i32_16x16x64_i8 v[126:129], v[132:135], v[164:167], v[126:129]
	v_mfma_i32_16x16x64_i8 v[102:105], v[140:143], v[164:167], v[102:105]
	v_mfma_i32_16x16x64_i8 v[122:125], v[132:135], v[172:175], v[122:125]
	v_mfma_i32_16x16x64_i8 v[94:97], v[140:143], v[172:175], v[94:97]
	v_mfma_i32_16x16x64_i8 v[118:121], v[132:135], v[180:183], v[118:121]
	v_mfma_i32_16x16x64_i8 v[46:49], v[140:143], v[180:183], v[46:49]
	v_mfma_i32_16x16x64_i8 v[110:113], v[132:135], v[196:199], v[110:113]
	v_mfma_i32_16x16x64_i8 v[38:41], v[140:143], v[196:199], v[38:41]
	v_mfma_i32_16x16x64_i8 v[126:129], v[136:139], v[168:171], v[126:129]
	v_mfma_i32_16x16x64_i8 v[102:105], v[144:147], v[168:171], v[102:105]
	v_mfma_i32_16x16x64_i8 v[122:125], v[136:139], v[176:179], v[122:125]
	v_mfma_i32_16x16x64_i8 v[94:97], v[144:147], v[176:179], v[94:97]
	v_mfma_i32_16x16x64_i8 v[118:121], v[136:139], v[190:193], v[118:121]
	v_mfma_i32_16x16x64_i8 v[46:49], v[144:147], v[190:193], v[46:49]
	v_mfma_i32_16x16x64_i8 v[110:113], v[136:139], v[200:203], v[110:113]
	v_mfma_i32_16x16x64_i8 v[38:41], v[144:147], v[200:203], v[38:41]
	v_mfma_i32_16x16x64_i8 v[114:117], v[148:151], v[164:167], v[114:117]
	v_mfma_i32_16x16x64_i8 v[82:85], v[156:159], v[164:167], v[82:85]
	v_mfma_i32_16x16x64_i8 v[106:109], v[148:151], v[172:175], v[106:109]
	v_mfma_i32_16x16x64_i8 v[74:77], v[156:159], v[172:175], v[74:77]
	v_mfma_i32_16x16x64_i8 v[98:101], v[148:151], v[180:183], v[98:101]
	v_mfma_i32_16x16x64_i8 v[42:45], v[156:159], v[180:183], v[42:45]
	v_mfma_i32_16x16x64_i8 v[90:93], v[148:151], v[196:199], v[90:93]
	v_mfma_i32_16x16x64_i8 v[34:37], v[156:159], v[196:199], v[34:37]
	v_mfma_i32_16x16x64_i8 v[114:117], v[152:155], v[168:171], v[114:117]
	v_mfma_i32_16x16x64_i8 v[82:85], v[160:163], v[168:171], v[82:85]
	v_mfma_i32_16x16x64_i8 v[106:109], v[152:155], v[176:179], v[106:109]
	v_mfma_i32_16x16x64_i8 v[74:77], v[160:163], v[176:179], v[74:77]
	v_mfma_i32_16x16x64_i8 v[98:101], v[152:155], v[190:193], v[98:101]
	v_mfma_i32_16x16x64_i8 v[42:45], v[160:163], v[190:193], v[42:45]
	v_mfma_i32_16x16x64_i8 v[90:93], v[152:155], v[200:203], v[90:93]
	v_mfma_i32_16x16x64_i8 v[34:37], v[160:163], v[200:203], v[34:37]
	s_barrier
	s_setprio 0
	ds_read_b128 v[164:167], v213 offset:49152
	ds_read_b128 v[168:171], v213 offset:50176
	ds_read_b128 v[172:175], v213 offset:51200
	ds_read_b128 v[176:179], v213 offset:52224
	ds_read_b128 v[180:183], v213 offset:53248
	ds_read_b128 v[190:193], v213 offset:54272
	ds_read_b128 v[196:199], v213 offset:55296
	ds_read_b128 v[200:203], v213 offset:56320
	s_add_u32 s98, s20, s76
	s_addc_u32 s99, s21, s77
	s_mov_b32 m0, s91
	s_nop 0
	global_load_lds_dwordx4 v130, s[98:99]
	s_add_u32 s100, s20, s78
	s_addc_u32 s101, s21, s79
	s_mov_b32 m0, s92
	s_nop 0
	global_load_lds_dwordx4 v130, s[100:101]
	s_add_u32 s98, s20, s80
	s_addc_u32 s99, s21, s81
	s_mov_b32 m0, s2
	s_nop 0
	global_load_lds_dwordx4 v130, s[98:99]
	s_add_u32 s100, s20, s82
	s_addc_u32 s101, s21, s83
	s_mov_b32 m0, s3
	s_nop 0
	global_load_lds_dwordx4 v130, s[100:101]
	s_add_u32 s98, s22, s76
	s_addc_u32 s99, s23, s77
	s_mov_b32 m0, s93
	s_nop 0
	global_load_lds_dwordx4 v130, s[98:99]
	s_add_u32 s100, s22, s78
	s_addc_u32 s101, s23, s79
	s_mov_b32 m0, s94
	s_nop 0
	global_load_lds_dwordx4 v130, s[100:101]
	s_waitcnt vmcnt(8)
	s_waitcnt lgkmcnt(0)
	s_setprio 1
	s_barrier
	v_mfma_i32_16x16x64_i8 v[86:89], v[132:135], v[164:167], v[86:89]
	v_mfma_i32_16x16x64_i8 v[30:33], v[140:143], v[164:167], v[30:33]
	v_mfma_i32_16x16x64_i8 v[78:81], v[132:135], v[172:175], v[78:81]
	v_mfma_i32_16x16x64_i8 v[22:25], v[140:143], v[172:175], v[22:25]
	v_mfma_i32_16x16x64_i8 v[70:73], v[132:135], v[180:183], v[70:73]
	v_mfma_i32_16x16x64_i8 v[14:17], v[140:143], v[180:183], v[14:17]
	v_mfma_i32_16x16x64_i8 v[62:65], v[132:135], v[196:199], v[62:65]
	v_mfma_i32_16x16x64_i8 v[2:5], v[140:143], v[196:199], v[2:5]
	v_mfma_i32_16x16x64_i8 v[86:89], v[136:139], v[168:171], v[86:89]
	v_mfma_i32_16x16x64_i8 v[30:33], v[144:147], v[168:171], v[30:33]
	v_mfma_i32_16x16x64_i8 v[78:81], v[136:139], v[176:179], v[78:81]
	v_mfma_i32_16x16x64_i8 v[22:25], v[144:147], v[176:179], v[22:25]
	v_mfma_i32_16x16x64_i8 v[70:73], v[136:139], v[190:193], v[70:73]
	v_mfma_i32_16x16x64_i8 v[14:17], v[144:147], v[190:193], v[14:17]
	v_mfma_i32_16x16x64_i8 v[62:65], v[136:139], v[200:203], v[62:65]
	v_mfma_i32_16x16x64_i8 v[2:5], v[144:147], v[200:203], v[2:5]
	v_mfma_i32_16x16x64_i8 v[66:69], v[148:151], v[164:167], v[66:69]
	v_mfma_i32_16x16x64_i8 v[26:29], v[156:159], v[164:167], v[26:29]
	v_mfma_i32_16x16x64_i8 v[58:61], v[148:151], v[172:175], v[58:61]
	v_mfma_i32_16x16x64_i8 v[18:21], v[156:159], v[172:175], v[18:21]
	v_mfma_i32_16x16x64_i8 v[54:57], v[148:151], v[180:183], v[54:57]
	v_mfma_i32_16x16x64_i8 v[10:13], v[156:159], v[180:183], v[10:13]
	v_mfma_i32_16x16x64_i8 v[50:53], v[148:151], v[196:199], v[50:53]
	v_mfma_i32_16x16x64_i8 v[6:9], v[156:159], v[196:199], v[6:9]
	v_mfma_i32_16x16x64_i8 v[66:69], v[152:155], v[168:171], v[66:69]
	v_mfma_i32_16x16x64_i8 v[26:29], v[160:163], v[168:171], v[26:29]
	v_mfma_i32_16x16x64_i8 v[58:61], v[152:155], v[176:179], v[58:61]
	v_mfma_i32_16x16x64_i8 v[18:21], v[160:163], v[176:179], v[18:21]
	v_mfma_i32_16x16x64_i8 v[54:57], v[152:155], v[190:193], v[54:57]
	v_mfma_i32_16x16x64_i8 v[10:13], v[160:163], v[190:193], v[10:13]
	v_mfma_i32_16x16x64_i8 v[50:53], v[152:155], v[200:203], v[50:53]
	v_mfma_i32_16x16x64_i8 v[6:9], v[160:163], v[200:203], v[6:9]
	s_barrier
	s_setprio 0
	s_add_i32 s14, s14, 2
	s_add_u32 s16, s16, 0x8000
	s_addc_u32 s17, s17, 0
	s_cmp_gt_u32 s14, 13
	s_mov_b64 s[28:29], s[30:31]
	s_cbranch_scc0 .LBB0_326
	v_readlane_b32 s14, v255, 11
	v_readlane_b32 s15, v255, 12
	s_and_b64 vcc, exec, s[14:15]
	s_cbranch_vccz .LBB0_329
	s_barrier
